# diff-attention main loop: lane-half exchange of the row maximum moved to the rescale path (threshold test needs no exchange)
# speedup vs baseline: 1.0235x; 1.0022x over previous
.LBB0_1126:
	s_lshl_b32 s4, s9, 1
	v_add_u32_e32 v216, s4, v247
	ds_read_b64_tr_b16 v[226:227], v216 offset:24576
	ds_read_b64_tr_b16 v[228:229], v216 offset:25088
	s_waitcnt lgkmcnt(9)
	v_mfma_f32_32x32x16_bf16 v[130:145], v[206:209], v[174:177], v[66:81]
	v_add_f32_e32 v1, v98, v99
	v_add_f32_e32 v1, v100, v1
	v_add_f32_e32 v1, v101, v1
	v_add_f32_e32 v1, v102, v1
	v_add_f32_e32 v1, v103, v1
	v_cvt_pk_bf16_f32 v158, v98, v99
	v_cvt_pk_bf16_f32 v159, v100, v101
	ds_read_b64_tr_b16 v[250:251], v216 offset:28672
	ds_read_b64_tr_b16 v[252:253], v216 offset:29184
	s_waitcnt lgkmcnt(10)
	v_mfma_f32_32x32x16_bf16 v[114:129], v[198:201], v[174:177], v[66:81]
	v_add_f32_e32 v1, v104, v1
	v_add_f32_e32 v1, v105, v1
	v_add_f32_e32 v1, v106, v1
	v_add_f32_e32 v1, v107, v1
	v_cvt_pk_bf16_f32 v160, v102, v103
	v_cvt_pk_bf16_f32 v161, v104, v105
	ds_read_b64_tr_b16 v[198:199], v216 offset:25600
	ds_read_b64_tr_b16 v[200:201], v216 offset:26112
	s_waitcnt lgkmcnt(11)
	v_mfma_f32_32x32x16_bf16 v[130:145], v[202:205], v[170:173], v[130:145]
	v_add_f32_e32 v1, v108, v1
	v_add_f32_e32 v1, v109, v1
	v_add_f32_e32 v1, v110, v1
	v_add_f32_e32 v1, v111, v1
	v_cvt_pk_bf16_f32 v154, v106, v107
	v_cvt_pk_bf16_f32 v155, v108, v109
	ds_read_b64_tr_b16 v[106:107], v216 offset:29696
	ds_read_b64_tr_b16 v[108:109], v216 offset:30208
	s_waitcnt lgkmcnt(12)
	v_mfma_f32_32x32x16_bf16 v[114:129], v[194:197], v[170:173], v[114:129]
	v_add_f32_e32 v1, v112, v1
	v_add_f32_e32 v1, v113, v1
	v_add_f32_e32 v1, v82, v1
	v_add_f32_e32 v1, v83, v1
	v_cvt_pk_bf16_f32 v156, v110, v111
	v_cvt_pk_bf16_f32 v157, v112, v113
	ds_read_b64_tr_b16 v[102:103], v216 offset:26624
	ds_read_b64_tr_b16 v[104:105], v216 offset:27136
	s_waitcnt lgkmcnt(13)
	v_mfma_f32_32x32x16_bf16 v[130:145], v[190:193], v[166:169], v[130:145]
	v_add_f32_e32 v1, v84, v1
	v_add_f32_e32 v1, v85, v1
	v_add_f32_e32 v1, v86, v1
	v_add_f32_e32 v1, v87, v1
	v_cvt_pk_bf16_f32 v150, v82, v83
	v_cvt_pk_bf16_f32 v151, v84, v85
	ds_read_b64_tr_b16 v[98:99], v216 offset:30720
	ds_read_b64_tr_b16 v[100:101], v216 offset:31232
	s_waitcnt lgkmcnt(14)
	v_mfma_f32_32x32x16_bf16 v[114:129], v[186:189], v[166:169], v[114:129]
	v_add_f32_e32 v1, v88, v1
	v_add_f32_e32 v1, v89, v1
	v_add_f32_e32 v1, v90, v1
	v_add_f32_e32 v1, v91, v1
	v_cvt_pk_bf16_f32 v152, v86, v87
	v_cvt_pk_bf16_f32 v153, v88, v89
	ds_read_b64_tr_b16 v[86:87], v216 offset:27648
	ds_read_b64_tr_b16 v[88:89], v216 offset:28160
	s_waitcnt lgkmcnt(14)
	v_mfma_f32_32x32x16_bf16 v[130:145], v[182:185], v[162:165], v[130:145]
	v_add_f32_e32 v1, v92, v1
	v_add_f32_e32 v1, v93, v1
	v_add_f32_e32 v1, v94, v1
	v_add_f32_e32 v1, v95, v1
	v_cvt_pk_bf16_f32 v146, v90, v91
	v_cvt_pk_bf16_f32 v147, v92, v93
	ds_read_b64_tr_b16 v[90:91], v216 offset:31744
	ds_read_b64_tr_b16 v[92:93], v216 offset:32256
	v_mfma_f32_32x32x16_bf16 v[114:129], v[178:181], v[162:165], v[114:129]
	v_add_f32_e32 v1, v96, v1
	v_add_f32_e32 v1, v97, v1
	v_cvt_pk_bf16_f32 v148, v94, v95
	v_cvt_pk_bf16_f32 v149, v96, v97
	s_add_i32 s4, s15, s55
	v_lshl_add_u64 v[82:83], v[212:213], 0, s[62:63]
	s_mov_b32 s8, m0
	s_mov_b32 m0, s4
	s_nop 0
	global_load_lds_dwordx4 v[82:83], off
	s_mov_b32 m0, s8
	s_lshl_b32 s4, s84, 1
	s_waitcnt lgkmcnt(14)
	v_mfma_f32_32x32x16_bf16 v[50:65], v[158:161], v[226:229], v[50:65]
	v_lshl_add_u64 v[82:83], v[214:215], 0, s[58:59]
	s_add_i32 s4, s4, s1
	s_mov_b32 s8, m0
	s_mov_b32 m0, s4
	s_nop 0
	global_load_lds_dwordx4 v[82:83], off
	s_mov_b32 m0, s8
	v_lshl_add_u64 v[82:83], v[214:215], 0, s[64:65]
	s_addk_i32 s4, 0x2000
	s_mov_b32 s8, m0
	s_mov_b32 m0, s4
	s_nop 0
	global_load_lds_dwordx4 v[82:83], off
	s_mov_b32 m0, s8
	ds_read_b64_tr_b16 v[206:207], v216 offset:32768
	ds_read_b64_tr_b16 v[208:209], v216 offset:33280
	s_waitcnt lgkmcnt(14)
	v_mfma_f32_32x32x16_bf16 v[34:49], v[158:161], v[250:253], v[34:49]
	ds_read_b64_tr_b16 v[110:111], v216 offset:36864
	ds_read_b64_tr_b16 v[112:113], v216 offset:37376
	s_waitcnt lgkmcnt(14)
	v_mfma_f32_32x32x16_bf16 v[50:65], v[154:157], v[198:201], v[50:65]
	ds_read_b64_tr_b16 v[94:95], v216 offset:33792
	ds_read_b64_tr_b16 v[96:97], v216 offset:34304
	v_max_f32_e32 v82, v130, v131
	v_max3_f32 v83, v132, v133, v115
	v_max3_f32 v82, v82, v114, v116
	v_max3_f32 v82, v82, v117, v134
	v_max3_f32 v83, v83, v136, v137
	v_max3_f32 v82, v82, v135, v118
	v_max3_f32 v83, v83, v120, v121
	v_max3_f32 v82, v82, v119, v138
	v_max3_f32 v83, v83, v140, v141
	v_max3_f32 v82, v82, v139, v122
	v_max3_f32 v83, v83, v124, v125
	v_max3_f32 v82, v82, v123, v142
	v_max3_f32 v83, v83, v144, v145
	v_max3_f32 v82, v82, v143, v126
	v_max3_f32 v83, v83, v128, v129
	v_max3_f32 v82, v82, v127, v83
	v_cmp_lt_f32_e32 vcc, s13, v82
	s_cmp_lg_u64 vcc, 0
	v_add_f32_e32 v1, v249, v1
	s_cselect_b64 s[86:87], -1, 0
	s_cbranch_vccnz .LBB0_1134

.LBB0_1129:
	s_add_i32 s4, s84, 0x2000
	s_cmpk_lg_i32 s84, 0x4000
	s_cselect_b32 s4, s4, 0
	s_lshl_b32 s8, s15, 1
	v_add_u32_e32 v226, s8, v247
	ds_read_b64_tr_b16 v[206:207], v226 offset:24576
	ds_read_b64_tr_b16 v[208:209], v226 offset:25088
	v_mfma_f32_32x32x16_bf16 v[98:113], v[82:85], v[174:177], v[66:81]
	v_add_f32_e32 v86, v130, v131
	v_add_f32_e32 v86, v132, v86
	v_add_f32_e32 v86, v133, v86
	v_add_f32_e32 v86, v134, v86
	v_add_f32_e32 v86, v135, v86
	v_cvt_pk_bf16_f32 v158, v130, v131
	v_cvt_pk_bf16_f32 v159, v132, v133
	ds_read_b64_tr_b16 v[250:251], v226 offset:28672
	ds_read_b64_tr_b16 v[252:253], v226 offset:29184
	v_add_f32_e32 v82, v136, v86
	v_add_f32_e32 v82, v137, v82
	v_add_f32_e32 v82, v138, v82
	v_add_f32_e32 v130, v139, v82
	v_mfma_f32_32x32x16_bf16 v[82:97], v[198:201], v[174:177], v[66:81]
	v_cvt_pk_bf16_f32 v160, v134, v135
	v_cvt_pk_bf16_f32 v161, v136, v137
	ds_read_b64_tr_b16 v[198:199], v226 offset:25600
	ds_read_b64_tr_b16 v[200:201], v226 offset:26112
	v_mfma_f32_32x32x16_bf16 v[98:113], v[202:205], v[170:173], v[98:113]
	v_add_f32_e32 v130, v140, v130
	v_add_f32_e32 v130, v141, v130
	v_add_f32_e32 v130, v142, v130
	v_add_f32_e32 v130, v143, v130
	v_cvt_pk_bf16_f32 v154, v138, v139
	v_cvt_pk_bf16_f32 v155, v140, v141
	ds_read_b64_tr_b16 v[138:139], v226 offset:29696
	ds_read_b64_tr_b16 v[140:141], v226 offset:30208
	v_mfma_f32_32x32x16_bf16 v[82:97], v[190:193], v[170:173], v[82:97]
	v_add_f32_e32 v130, v144, v130
	v_add_f32_e32 v130, v145, v130
	v_add_f32_e32 v130, v114, v130
	v_add_f32_e32 v130, v115, v130
	v_cvt_pk_bf16_f32 v156, v142, v143
	v_cvt_pk_bf16_f32 v157, v144, v145
	ds_read_b64_tr_b16 v[134:135], v226 offset:26624
	ds_read_b64_tr_b16 v[136:137], v226 offset:27136
	v_mfma_f32_32x32x16_bf16 v[98:113], v[194:197], v[166:169], v[98:113]
	v_add_f32_e32 v130, v116, v130
	v_add_f32_e32 v130, v117, v130
	v_add_f32_e32 v130, v118, v130
	v_add_f32_e32 v142, v119, v130
	v_cvt_pk_bf16_f32 v150, v114, v115
	v_cvt_pk_bf16_f32 v151, v116, v117
	ds_read_b64_tr_b16 v[130:131], v226 offset:30720
	ds_read_b64_tr_b16 v[132:133], v226 offset:31232
	v_mfma_f32_32x32x16_bf16 v[82:97], v[182:185], v[166:169], v[82:97]
	v_add_f32_e32 v114, v120, v142
	v_add_f32_e32 v114, v121, v114
	v_add_f32_e32 v114, v122, v114
	v_add_f32_e32 v142, v123, v114
	v_cvt_pk_bf16_f32 v152, v118, v119
	v_cvt_pk_bf16_f32 v153, v120, v121
	ds_read_b64_tr_b16 v[114:115], v226 offset:27648
	ds_read_b64_tr_b16 v[116:117], v226 offset:28160
	v_mfma_f32_32x32x16_bf16 v[98:113], v[186:189], v[162:165], v[98:113]
	v_add_f32_e32 v118, v124, v142
	v_add_f32_e32 v118, v125, v118
	v_add_f32_e32 v118, v126, v118
	v_add_f32_e32 v142, v127, v118
	v_cvt_pk_bf16_f32 v146, v122, v123
	v_cvt_pk_bf16_f32 v147, v124, v125
	ds_read_b64_tr_b16 v[118:119], v226 offset:31744
	ds_read_b64_tr_b16 v[120:121], v226 offset:32256
	v_mfma_f32_32x32x16_bf16 v[82:97], v[178:181], v[162:165], v[82:97]
	v_add_f32_e32 v122, v128, v142
	v_add_f32_e32 v122, v129, v122
	v_add_f32_e32 v178, 0, v122
	v_cvt_pk_bf16_f32 v148, v126, v127
	v_cvt_pk_bf16_f32 v149, v128, v129
	s_mov_b64 s[8:9], 0x180000
	v_lshl_add_u64 v[122:123], v[212:213], 0, s[8:9]
	s_add_i32 s8, s84, s55
	s_mov_b32 s9, m0
	s_mov_b32 m0, s8
	s_nop 0
	global_load_lds_dwordx4 v[122:123], off
	s_mov_b32 m0, s9
	s_lshl_b32 s8, s4, 1
	s_waitcnt lgkmcnt(14)
	v_mfma_f32_32x32x16_bf16 v[50:65], v[158:161], v[206:209], v[50:65]
	v_lshl_add_u64 v[216:217], v[214:215], 0, s[60:61]
	s_add_i32 s8, s8, s1
	s_mov_b32 s9, m0
	s_mov_b32 m0, s8
	s_nop 0
	global_load_lds_dwordx4 v[216:217], off
	s_mov_b32 m0, s9
	v_lshl_add_u64 v[122:123], v[214:215], 0, s[66:67]
	s_addk_i32 s8, 0x2000
	s_mov_b32 s9, m0
	s_mov_b32 m0, s8
	s_nop 0
	global_load_lds_dwordx4 v[122:123], off
	s_mov_b32 m0, s9
	ds_read_b64_tr_b16 v[142:143], v226 offset:32768
	ds_read_b64_tr_b16 v[144:145], v226 offset:33280
	s_waitcnt lgkmcnt(14)
	v_mfma_f32_32x32x16_bf16 v[34:49], v[158:161], v[250:253], v[34:49]
	ds_read_b64_tr_b16 v[126:127], v226 offset:36864
	ds_read_b64_tr_b16 v[128:129], v226 offset:37376
	s_waitcnt lgkmcnt(14)
	v_mfma_f32_32x32x16_bf16 v[50:65], v[154:157], v[198:201], v[50:65]
	ds_read_b64_tr_b16 v[122:123], v226 offset:33792
	ds_read_b64_tr_b16 v[124:125], v226 offset:34304
	v_max_f32_e32 v179, v98, v99
	v_max3_f32 v180, v100, v101, v83
	v_max3_f32 v179, v179, v82, v84
	v_max3_f32 v179, v179, v85, v102
	v_max3_f32 v180, v180, v104, v105
	v_max3_f32 v179, v179, v103, v86
	v_max3_f32 v180, v180, v88, v89
	v_max3_f32 v179, v179, v87, v106
	v_max3_f32 v180, v180, v108, v109
	v_max3_f32 v179, v179, v107, v90
	v_max3_f32 v180, v180, v92, v93
	v_max3_f32 v179, v179, v91, v110
	v_max3_f32 v180, v180, v112, v113
	v_max3_f32 v179, v179, v111, v94
	v_max3_f32 v180, v180, v96, v97
	v_add_f32_e32 v249, v1, v178
	v_max3_f32 v1, v179, v95, v180
	v_cmp_lt_f32_e32 vcc, s13, v1
	s_cmp_lg_u64 vcc, 0
	s_cselect_b64 s[86:87], -1, 0
	s_cbranch_vccnz .LBB0_1137

.LBB0_1134:
	v_mov_b32_e32 v83, v82
	s_nop 1
	v_permlane32_swap_b32_e32 v82, v83
	v_max_f32_e32 v82, v82, v83
	v_max_f32_e32 v66, v82, v82
	v_max_f32_e32 v82, 0, v66
	v_exp_f32_e64 v83, -v82
	v_add_f32_e32 v246, v246, v82
	v_xor_b32_e32 v66, 0x80000000, v246
	v_mov_b32_e32 v67, v66
	v_mov_b32_e32 v68, v66
	v_mov_b32_e32 v69, v66
	v_mov_b32_e32 v70, v66
	v_mov_b32_e32 v71, v66
	v_mov_b32_e32 v72, v66
	v_mov_b32_e32 v73, v66
	v_mov_b32_e32 v74, v66
	v_mov_b32_e32 v75, v66
	v_mov_b32_e32 v76, v66
	v_mov_b32_e32 v77, v66
	v_mov_b32_e32 v78, v66
	v_mov_b32_e32 v79, v66
	v_mov_b32_e32 v80, v66
	v_mov_b32_e32 v81, v66
	s_and_saveexec_b64 s[88:89], s[6:7]
	ds_write_b32 v243, v83
	s_or_b64 exec, exec, s[88:89]
	v_sub_f32_e32 v145, v145, v82
	v_sub_f32_e32 v144, v144, v82
	v_sub_f32_e32 v143, v143, v82
	v_sub_f32_e32 v142, v142, v82
	v_sub_f32_e32 v141, v141, v82
	v_sub_f32_e32 v140, v140, v82
	v_sub_f32_e32 v139, v139, v82
	v_sub_f32_e32 v138, v138, v82
	v_sub_f32_e32 v137, v137, v82
	v_sub_f32_e32 v136, v136, v82
	v_sub_f32_e32 v135, v135, v82
	v_sub_f32_e32 v134, v134, v82
	v_sub_f32_e32 v133, v133, v82
	v_sub_f32_e32 v132, v132, v82
	v_sub_f32_e32 v131, v131, v82
	v_sub_f32_e32 v130, v130, v82
	v_sub_f32_e32 v129, v129, v82
	v_sub_f32_e32 v128, v128, v82
	v_sub_f32_e32 v127, v127, v82
	v_sub_f32_e32 v126, v126, v82
	v_sub_f32_e32 v125, v125, v82
	v_sub_f32_e32 v124, v124, v82
	v_sub_f32_e32 v123, v123, v82
	v_sub_f32_e32 v122, v122, v82
	v_sub_f32_e32 v121, v121, v82
	v_sub_f32_e32 v120, v120, v82
	v_sub_f32_e32 v119, v119, v82
	v_sub_f32_e32 v118, v118, v82
	v_sub_f32_e32 v117, v117, v82
	v_sub_f32_e32 v116, v116, v82
	v_sub_f32_e32 v115, v115, v82
	v_sub_f32_e32 v114, v114, v82
	v_mul_f32_e32 v1, v1, v83
	s_branch .LBB0_1127
.LBB0_1137:
	v_mov_b32_e32 v178, v1
	s_nop 1
	v_permlane32_swap_b32_e32 v1, v178
	v_max_f32_e32 v1, v1, v178
	v_max_f32_e32 v1, v1, v1
	v_max_f32_e32 v1, 0, v1
	v_exp_f32_e64 v178, -v1
	v_add_f32_e32 v246, v246, v1
	v_xor_b32_e32 v66, 0x80000000, v246
	v_mov_b32_e32 v67, v66
	v_mov_b32_e32 v68, v66
	v_mov_b32_e32 v69, v66
	v_mov_b32_e32 v70, v66
	v_mov_b32_e32 v71, v66
	v_mov_b32_e32 v72, v66
	v_mov_b32_e32 v73, v66
	v_mov_b32_e32 v74, v66
	v_mov_b32_e32 v75, v66
	v_mov_b32_e32 v76, v66
	v_mov_b32_e32 v77, v66
	v_mov_b32_e32 v78, v66
	v_mov_b32_e32 v79, v66
	v_mov_b32_e32 v80, v66
	v_mov_b32_e32 v81, v66
	s_and_saveexec_b64 s[88:89], s[6:7]
	ds_write_b32 v243, v178
	s_or_b64 exec, exec, s[88:89]
	v_sub_f32_e32 v113, v113, v1
	v_sub_f32_e32 v112, v112, v1
	v_sub_f32_e32 v111, v111, v1
	v_sub_f32_e32 v110, v110, v1
	v_sub_f32_e32 v109, v109, v1
	v_sub_f32_e32 v108, v108, v1
	v_sub_f32_e32 v107, v107, v1
	v_sub_f32_e32 v106, v106, v1
	v_sub_f32_e32 v105, v105, v1
	v_sub_f32_e32 v104, v104, v1
	v_sub_f32_e32 v103, v103, v1
	v_sub_f32_e32 v102, v102, v1
	v_sub_f32_e32 v101, v101, v1
	v_sub_f32_e32 v100, v100, v1
	v_sub_f32_e32 v99, v99, v1
	v_sub_f32_e32 v98, v98, v1
	v_sub_f32_e32 v97, v97, v1
	v_sub_f32_e32 v96, v96, v1
	v_sub_f32_e32 v95, v95, v1
	v_sub_f32_e32 v94, v94, v1
	v_sub_f32_e32 v93, v93, v1
	v_sub_f32_e32 v92, v92, v1
	v_sub_f32_e32 v91, v91, v1
	v_sub_f32_e32 v90, v90, v1
	v_sub_f32_e32 v89, v89, v1
	v_sub_f32_e32 v88, v88, v1
	v_sub_f32_e32 v87, v87, v1
	v_sub_f32_e32 v86, v86, v1
	v_sub_f32_e32 v85, v85, v1
	v_sub_f32_e32 v84, v84, v1
	v_sub_f32_e32 v83, v83, v1
	v_sub_f32_e32 v82, v82, v1
	v_mul_f32_e32 v249, v249, v178
	s_branch .LBB0_1130
